# layer-0 context-row output projection: split-K reduced from 8 parts x K256 to 2 parts x K1024 (4x fewer float atomics, which were throughput-bound)
# speedup vs baseline: 1.0805x; 1.0230x over previous
; __device__ __forceinline__ PRef getp() { const __attribute__((address_space(4))) Params* kp = (const __attribute__((address_space(4))) Params*)__builtin_amdgcn_kernarg_segment_ptr(); asm volatile("" : "+s"(kp)); return *kp; }
; #define PG8_STAGE(bufoff, gbase, voff) do { _Pragma("unroll") for (int _i = 0; _i < 2; ++_i) \
;         __builtin_amdgcn_global_load_lds((const unsigned*)((const char*)(gbase) + (size_t)_i * r64##voff + (voff)), (LAS unsigned*)(lds + (bufoff) + ldsw + _i * 8192), 16, 0, 0); } while (0)
; #define PG8_WAIT_V(n) asm volatile("s_waitcnt vmcnt(" #n ")" ::: "memory")
; #define PG8_BAR __builtin_amdgcn_s_barrier()
; #define mod ((const float*)(getp().ws + O_MOD))
; #define hctx ((float*)(getp().ws + O_HCTX))
; template <class Epi, class Sched>
; __device__ __forceinline__ void gemm_phase(LAS unsigned char* lds, const Gemm g, const Sched& S, const Epi& E) {
;     ...
;     const char* cA = (const char*)g.A + (size_t)cur.pm * tstepA; const char* cB = (const char*)g.Bt + (size_t)cur.pn * tstepB;
;     PG8_STAGE(PG8_SB(0, 0), cB, voffB); PG8_STAGE(PG8_SA(0, 0), cA, voffA); PG8_STAGE(PG8_SB(0, 1), cB + hstepB, voffB); PG8_STAGE(PG8_SA(0, 1), cA + hstepA, voffA);
;     if (wr == 1) PG8_BAR;
;     PG8_WAIT_V(4); PG8_BAR;
;     PG8_STAGE(PG8_SB(1, 0), cB + kstep, voffB); PG8_STAGE(PG8_SA(1, 0), cA + kstep, voffA); PG8_STAGE(PG8_SB(1, 1), cB + hstepB + kstep, voffB);
;     PG8_WAIT_V(6); PG8_BAR;
; __global__ void __launch_bounds__(512, 2) fwd_megakernel(Params p_) {
;     ...
;         if (layer == 0) {
;             for (int L2 = blockIdx.x; L2 < 256; L2 += gridDim.x) { const int part = L2 & 7, uu = L2 >> 3; pg8::SingleOrder S1{RL / 256 + (uu & 3), uu >> 2, true};
;             pg8::Gemm g{XN + part * 256, (const bf16_t*)(getp().ws + O_WT_OUT) + part * 256, RT, 2048, 256, 2048, 2048};
;             EpiResidAtomic E{hctx, mod + (size_t)(layer * 5 + 4) * 12288 + 2 * 2048}; pg8::gemm_phase(lds, g, S1, E); }
.LBB0_479:
	s_cmpk_gt_i32 s84, 0x3f
	s_cbranch_scc1 .LBB0_488
	s_mov_b32 s3, 0
	v_mov_b32_e32 v129, 0
	s_mov_b64 s[4:5], 0x40000
	s_mov_b64 s[6:7], 0x80000
	s_mov_b64 s[8:9], 0xc0000
	s_mov_b64 s[10:11], 0x80
	s_mov_b64 s[16:17], 0x40080
	s_mov_b64 s[18:19], 0x80080
	s_mov_b64 s[20:21], 0xc0080
	s_mov_b64 s[22:23], 0x100000
	s_mov_b32 s13, 0x100000
	s_mov_b64 s[24:25], 0x120000
	s_mov_b32 s14, 0x120000
	s_mov_b64 s[26:27], 0x140000
	s_mov_b32 s28, 0x140000
	s_mov_b64 s[42:43], 0x160000
	s_mov_b32 s29, 0x160000
	v_mov_b32_e32 v136, 1
	s_add_i32 s30, 0, 0x10000
	s_add_i32 s31, 0, 0x14000
	s_mov_b32 s33, s84
	s_movk_i32 s62, 0x100
	s_branch .LBB0_482
.LBB0_481:
	s_add_i32 s33, s33, s15
	s_cmpk_lt_i32 s33, 0x40
	s_barrier
	s_cbranch_scc0 .LBB0_488
.LBB0_482:
	s_mov_b64 s[34:35], s[0:1]
	s_mov_b64 s[36:37], s[0:1]
	s_mov_b64 s[50:51], s[0:1]
	s_mov_b64 s[52:53], s[0:1]
	v_mov_b32_e32 v4, v222
	s_load_dwordx2 s[34:35], s[34:35], 0x120
	s_bfe_u32 s2, s33, 0x20001
	v_bfe_i32 v3, v4, 27, 1
	v_lshlrev_b32_e32 v2, 4, v4
	v_lshrrev_b32_e32 v3, 22, v3
	s_load_dwordx2 s[36:37], s[36:37], 0x120
	v_add_u32_e32 v3, v2, v3
	s_or_b32 s12, s2, 64
	s_lshl_b32 s2, s33, 11
	v_and_b32_e32 v3, 0xfffffc00, v3
	s_ashr_i32 s44, s33, 3
	s_and_b32 s2, s2, 0x800
	v_sub_u32_e32 v2, v2, v3
	s_waitcnt lgkmcnt(0)
	s_add_u32 s38, s34, s2
	v_lshrrev_b32_e32 v3, 4, v2
	s_addc_u32 s39, s35, 0
	v_bitop3_b32 v3, v3, v2, 32 bitop3:0x6c
	v_ashrrev_i32_e32 v2, 31, v2
	s_add_u32 s41, s36, s2
	v_readfirstlane_b32 s34, v4
	v_ashrrev_i32_e32 v0, 31, v4
	v_lshrrev_b32_e32 v2, 26, v2
	s_addc_u32 s46, s37, 0
	s_ashr_i32 s2, s34, 6
	v_lshrrev_b32_e32 v0, 26, v0
	v_add_u32_e32 v2, v3, v2
	s_ashr_i32 s45, s44, 31
	s_ashr_i32 s40, s34, 8
	s_lshl_b32 s35, s2, 10
	v_add_u32_e32 v0, v4, v0
	v_ashrrev_i32_e32 v2, 6, v2
	s_lshl_b32 s48, s12, 20
	s_lshl_b64 s[36:37], s[44:45], 20
	v_ashrrev_i32_e32 v0, 6, v0
	v_mul_i32_i24_e32 v5, 64, v2
	s_add_u32 s36, s41, s36
	v_lshlrev_b32_e32 v1, 5, v0
	v_sub_u32_e32 v3, v3, v5
	v_lshlrev_b32_e32 v0, 3, v0
	s_addc_u32 s37, s46, s37
	v_and_b32_e32 v1, 32, v1
	v_ashrrev_i16_sdwa v3, v136, sext(v3) dst_sel:DWORD dst_unused:UNUSED_PAD src0_sel:DWORD src1_sel:BYTE_0
	v_and_b32_e32 v0, 0xffff0, v0
	s_add_u32 s46, s36, 0x1400000
	v_add_u32_sdwa v1, v1, sext(v3) dst_sel:DWORD dst_unused:UNUSED_PAD src0_sel:DWORD src1_sel:WORD_0
	v_add_lshl_u32 v0, v2, v0, 12
	s_addc_u32 s47, s37, 0
	s_add_i32 s36, s35, 0
	v_lshl_add_u32 v128, v1, 1, v0
	s_add_i32 m0, s36, 0x10000
	v_lshl_add_u64 v[0:1], s[46:47], 0, v[128:129]
	global_load_lds_dwordx4 v128, s[46:47]
	s_add_i32 m0, s36, 0x12000
	s_add_u32 s37, s38, s48
	s_addc_u32 s38, s39, 0
	s_add_u32 s48, s37, 0xcf24000
	v_lshl_add_u64 v[2:3], v[0:1], 0, s[4:5]
	s_addc_u32 s49, s38, 0
	global_load_lds_dwordx4 v[2:3], off
	v_lshl_add_u64 v[2:3], s[48:49], 0, v[128:129]
	s_mov_b32 m0, s36
	s_add_i32 s37, s36, 0x2000
	global_load_lds_dwordx4 v128, s[48:49]
	v_lshl_add_u64 v[6:7], v[2:3], 0, s[4:5]
	s_mov_b32 m0, s37
	s_add_i32 s38, s36, 0x4000
	global_load_lds_dwordx4 v[6:7], off
	v_lshl_add_u64 v[6:7], v[0:1], 0, s[6:7]
	s_add_i32 m0, s36, 0x14000
	v_lshl_add_u64 v[130:131], v[2:3], 0, s[6:7]
	global_load_lds_dwordx4 v[6:7], off
	v_lshl_add_u64 v[6:7], v[0:1], 0, s[8:9]
	s_add_i32 m0, s36, 0x16000
	s_add_i32 s39, s36, 0x6000
	global_load_lds_dwordx4 v[6:7], off
	s_mov_b32 m0, s38
	v_lshl_add_u64 v[6:7], v[2:3], 0, s[8:9]
	global_load_lds_dwordx4 v[130:131], off
	s_mov_b32 m0, s39
	s_cmp_lg_u32 s40, 1
	global_load_lds_dwordx4 v[6:7], off
	s_cbranch_scc1 .LBB0_484
	s_barrier

; #define PG8_STAGE(bufoff, gbase, voff) do { _Pragma("unroll") for (int _i = 0; _i < 2; ++_i) \
;         __builtin_amdgcn_global_load_lds((const unsigned*)((const char*)(gbase) + (size_t)_i * r64##voff + (voff)), (LAS unsigned*)(lds + (bufoff) + ldsw + _i * 8192), 16, 0, 0); } while (0)
; #define PG8_LDA(dst, b, h) do { _Pragma("unroll") for (int m = 0; m < 4; ++m) _Pragma("unroll") for (int k = 0; k < 2; ++k) dst[m][k] = *(const LAS bf16x8*)(lds + PG8_SA(b, h) + aoff + m * 2048 + k * 1024); } while (0)
; #define PG8_LDB(dst, b, h) do { _Pragma("unroll") for (int n = 0; n < 2; ++n) _Pragma("unroll") for (int k = 0; k < 2; ++k) dst[n][k] = *(const LAS bf16x8*)(lds + PG8_SB(b, h) + boff + n * 2048 + k * 1024); } while (0)
; #define PG8_MMA(ai, bj, At, Bt) do { __builtin_amdgcn_s_setprio(1); _Pragma("unroll") for (int m = 0; m < 4; ++m) _Pragma("unroll") for (int n = 0; n < 2; ++n) _Pragma("unroll") for (int k = 0; k < 2; ++k) \
;         acc[ai][bj][m][n] = __builtin_amdgcn_mfma_f32_16x16x32_bf16(Bt[n][k], At[m][k], acc[ai][bj][m][n], 0, 0, 0); __builtin_amdgcn_s_setprio(0); } while (0)
; #define PG8_WAIT_V(n) asm volatile("s_waitcnt vmcnt(" #n ")" ::: "memory")
; #define PG8_WAIT_L(n) asm volatile("s_waitcnt lgkmcnt(" #n ")" ::: "memory")
; template <class Epi, class Sched>
; __device__ __forceinline__ void gemm_phase(LAS unsigned char* lds, const Gemm g, const Sched& S, const Epi& E) {
;     ...
;         for (int t = 0; t < nt; t += 2) {
;             const bool last = (t == nt - 2);
;             const char* a1 = cA + (size_t)(t + 1) * kstep;
;             const char* a2 = last ? nA : cA + (size_t)(t + 2) * kstep; const char* b2 = last ? nB : cB + (size_t)(t + 2) * kstep;
;             const char* a3 = a2 + kstep; const char* b3 = b2 + kstep;
;             PG8_LDB(B0, 0, 0); PG8_SCHED; PG8_LDA(At, 0, 0); PG8_STAGE(PG8_SA(1, 1), a1 + hstepA, voffA);
;             PG8_WAIT_L(8); PG8_BAR; PG8_WAIT_L(0); PG8_MMA(0, 0, At, B0); PG8_BAR; PG8_SCHED;
;             PG8_LDB(B1, 0, 1); PG8_STAGE(PG8_SB(0, 0), b2, voffB);
;             PG8_BAR; PG8_WAIT_L(0); PG8_MMA(0, 1, At, B1); PG8_BAR;
;             PG8_LDA(At, 0, 1); PG8_STAGE(PG8_SA(0, 0), a2, voffA);
;             PG8_BAR; PG8_WAIT_L(0); PG8_MMA(1, 0, At, B0); PG8_BAR; PG8_SCHED;
;             PG8_STAGE(PG8_SB(0, 1), b2 + hstepB, voffB);
;             PG8_WAIT_V(6); PG8_BAR; PG8_MMA(1, 1, At, B1); PG8_BAR;
.LBB0_485:
	s_add_i32 s58, s2, 0x100
	s_and_b64 s[56:57], s[56:57], exec
	ds_read_b128 v[138:141], v134
	ds_read_b128 v[142:145], v134 offset:1024
	ds_read_b128 v[146:149], v134 offset:2048
	ds_read_b128 v[150:153], v134 offset:3072
	s_cselect_b32 s58, 0, s58
	s_cselect_b32 s59, 0, 0
	s_add_u32 s56, s48, s58
	s_addc_u32 s57, s49, s59
	s_add_u32 s58, s46, s58
	s_addc_u32 s59, s47, s59
	s_add_i32 s65, 0, 0x18000
	s_add_i32 s63, 0, 0x1c000
	s_add_i32 s68, s31, s35
	s_add_i32 s64, s65, s35
	s_add_i32 s69, s63, s35
	s_add_i32 s70, s61, 0x2000
	s_add_i32 s66, s68, 0x2000
	s_add_i32 s71, s64, 0x2000
	s_add_i32 s67, s69, 0x2000
	v_lshl_add_u64 v[186:187], v[130:131], 0, s[2:3]
	s_mov_b32 m0, s45
	v_lshl_add_u64 v[188:189], v[186:187], 0, s[10:11]
	ds_read_b128 v[154:157], v133
	ds_read_b128 v[158:161], v133 offset:1024
	ds_read_b128 v[162:165], v133 offset:2048
	ds_read_b128 v[166:169], v133 offset:3072
	ds_read_b128 v[170:173], v133 offset:4096
	ds_read_b128 v[174:177], v133 offset:5120
	ds_read_b128 v[178:181], v133 offset:6144
	ds_read_b128 v[182:185], v133 offset:7168
	global_load_lds_dwordx4 v[188:189], off
	v_lshl_add_u64 v[186:187], v[186:187], 0, s[16:17]
	s_mov_b32 m0, s60
	s_nop 0
	global_load_lds_dwordx4 v[186:187], off
	s_waitcnt lgkmcnt(8)
	s_barrier
	s_waitcnt lgkmcnt(0)
	s_setprio 1
	s_waitcnt lgkmcnt(0)
	v_mfma_f32_16x16x32_bf16 v[124:127], v[138:141], v[154:157], v[124:127]
	v_mfma_f32_16x16x32_bf16 v[120:123], v[146:149], v[154:157], v[120:123]
	v_mfma_f32_16x16x32_bf16 v[112:115], v[138:141], v[162:165], v[112:115]
	v_mfma_f32_16x16x32_bf16 v[104:107], v[146:149], v[162:165], v[104:107]
	v_mfma_f32_16x16x32_bf16 v[96:99], v[138:141], v[170:173], v[96:99]
	v_mfma_f32_16x16x32_bf16 v[88:91], v[146:149], v[170:173], v[88:91]
	v_mfma_f32_16x16x32_bf16 v[80:83], v[138:141], v[178:181], v[80:83]
	v_mfma_f32_16x16x32_bf16 v[72:75], v[146:149], v[178:181], v[72:75]
	v_mfma_f32_16x16x32_bf16 v[124:127], v[142:145], v[158:161], v[124:127]
	v_mfma_f32_16x16x32_bf16 v[120:123], v[150:153], v[158:161], v[120:123]
	v_mfma_f32_16x16x32_bf16 v[112:115], v[142:145], v[166:169], v[112:115]
	v_mfma_f32_16x16x32_bf16 v[104:107], v[150:153], v[166:169], v[104:107]
	v_mfma_f32_16x16x32_bf16 v[96:99], v[142:145], v[174:177], v[96:99]
	v_mfma_f32_16x16x32_bf16 v[88:91], v[150:153], v[174:177], v[88:91]
	v_mfma_f32_16x16x32_bf16 v[80:83], v[142:145], v[182:185], v[80:83]
	v_mfma_f32_16x16x32_bf16 v[72:75], v[150:153], v[182:185], v[72:75]
	s_setprio 0
	s_barrier
	s_mov_b32 m0, s61
	v_lshl_add_u64 v[202:203], s[58:59], 0, v[128:129]
	ds_read_b128 v[186:189], v135
	ds_read_b128 v[190:193], v135 offset:1024
	ds_read_b128 v[194:197], v135 offset:2048
	ds_read_b128 v[198:201], v135 offset:3072
	global_load_lds_dwordx4 v[202:203], off
	v_lshl_add_u64 v[204:205], v[202:203], 0, s[4:5]
	s_mov_b32 m0, s70
	s_nop 0
	global_load_lds_dwordx4 v[204:205], off
	s_barrier
	s_waitcnt lgkmcnt(0)
	s_setprio 1
	s_waitcnt lgkmcnt(0)
	v_mfma_f32_16x16x32_bf16 v[116:119], v[186:189], v[154:157], v[116:119]
	v_mfma_f32_16x16x32_bf16 v[108:111], v[194:197], v[154:157], v[108:111]
	v_mfma_f32_16x16x32_bf16 v[100:103], v[186:189], v[162:165], v[100:103]
	v_mfma_f32_16x16x32_bf16 v[92:95], v[194:197], v[162:165], v[92:95]
	v_mfma_f32_16x16x32_bf16 v[84:87], v[186:189], v[170:173], v[84:87]
	v_mfma_f32_16x16x32_bf16 v[76:79], v[194:197], v[170:173], v[76:79]
	v_mfma_f32_16x16x32_bf16 v[68:71], v[186:189], v[178:181], v[68:71]
	v_mfma_f32_16x16x32_bf16 v[64:67], v[194:197], v[178:181], v[64:67]
	v_mfma_f32_16x16x32_bf16 v[116:119], v[190:193], v[158:161], v[116:119]
	v_mfma_f32_16x16x32_bf16 v[108:111], v[198:201], v[158:161], v[108:111]
	v_mfma_f32_16x16x32_bf16 v[100:103], v[190:193], v[166:169], v[100:103]
	v_mfma_f32_16x16x32_bf16 v[92:95], v[198:201], v[166:169], v[92:95]
	v_mfma_f32_16x16x32_bf16 v[84:87], v[190:193], v[174:177], v[84:87]
	v_mfma_f32_16x16x32_bf16 v[76:79], v[198:201], v[174:177], v[76:79]
	v_mfma_f32_16x16x32_bf16 v[68:71], v[190:193], v[182:185], v[68:71]
	v_mfma_f32_16x16x32_bf16 v[64:67], v[198:201], v[182:185], v[64:67]
	s_setprio 0
	s_mov_b32 m0, s36
	v_lshl_add_u64 v[204:205], s[56:57], 0, v[128:129]
	s_barrier
	ds_read_b128 v[154:157], v133 offset:16384
	ds_read_b128 v[158:161], v133 offset:17408
	ds_read_b128 v[162:165], v133 offset:18432
	ds_read_b128 v[166:169], v133 offset:19456
	ds_read_b128 v[170:173], v133 offset:20480
	ds_read_b128 v[174:177], v133 offset:21504
	ds_read_b128 v[178:181], v133 offset:22528
	ds_read_b128 v[182:185], v133 offset:23552
	global_load_lds_dwordx4 v[204:205], off
	v_lshl_add_u64 v[206:207], v[204:205], 0, s[4:5]
	s_mov_b32 m0, s37
	s_nop 0
	global_load_lds_dwordx4 v[206:207], off
	s_barrier
	s_waitcnt lgkmcnt(0)
	s_setprio 1
	s_waitcnt lgkmcnt(0)
	v_mfma_f32_16x16x32_bf16 v[60:63], v[138:141], v[154:157], v[60:63]
	v_mfma_f32_16x16x32_bf16 v[56:59], v[146:149], v[154:157], v[56:59]
	v_mfma_f32_16x16x32_bf16 v[48:51], v[138:141], v[162:165], v[48:51]
	v_mfma_f32_16x16x32_bf16 v[40:43], v[146:149], v[162:165], v[40:43]
	v_mfma_f32_16x16x32_bf16 v[32:35], v[138:141], v[170:173], v[32:35]
	v_mfma_f32_16x16x32_bf16 v[24:27], v[146:149], v[170:173], v[24:27]
	v_mfma_f32_16x16x32_bf16 v[16:19], v[138:141], v[178:181], v[16:19]
	v_mfma_f32_16x16x32_bf16 v[8:11], v[146:149], v[178:181], v[8:11]
	v_mfma_f32_16x16x32_bf16 v[60:63], v[142:145], v[158:161], v[60:63]
	v_mfma_f32_16x16x32_bf16 v[56:59], v[150:153], v[158:161], v[56:59]
	v_mfma_f32_16x16x32_bf16 v[48:51], v[142:145], v[166:169], v[48:51]
	v_mfma_f32_16x16x32_bf16 v[40:43], v[150:153], v[166:169], v[40:43]
	v_mfma_f32_16x16x32_bf16 v[32:35], v[142:145], v[174:177], v[32:35]
	v_mfma_f32_16x16x32_bf16 v[24:27], v[150:153], v[174:177], v[24:27]
	v_mfma_f32_16x16x32_bf16 v[16:19], v[142:145], v[182:185], v[16:19]
	v_mfma_f32_16x16x32_bf16 v[8:11], v[150:153], v[182:185], v[8:11]
	s_setprio 0
	s_barrier
; #define PG8_STAGE(bufoff, gbase, voff) do { _Pragma("unroll") for (int _i = 0; _i < 2; ++_i) \
;         __builtin_amdgcn_global_load_lds((const unsigned*)((const char*)(gbase) + (size_t)_i * r64##voff + (voff)), (LAS unsigned*)(lds + (bufoff) + ldsw + _i * 8192), 16, 0, 0); } while (0)
; #define PG8_LDA(dst, b, h) do { _Pragma("unroll") for (int m = 0; m < 4; ++m) _Pragma("unroll") for (int k = 0; k < 2; ++k) dst[m][k] = *(const LAS bf16x8*)(lds + PG8_SA(b, h) + aoff + m * 2048 + k * 1024); } while (0)
; #define PG8_LDB(dst, b, h) do { _Pragma("unroll") for (int n = 0; n < 2; ++n) _Pragma("unroll") for (int k = 0; k < 2; ++k) dst[n][k] = *(const LAS bf16x8*)(lds + PG8_SB(b, h) + boff + n * 2048 + k * 1024); } while (0)
; #define PG8_MMA(ai, bj, At, Bt) do { __builtin_amdgcn_s_setprio(1); _Pragma("unroll") for (int m = 0; m < 4; ++m) _Pragma("unroll") for (int n = 0; n < 2; ++n) _Pragma("unroll") for (int k = 0; k < 2; ++k) \
;         acc[ai][bj][m][n] = __builtin_amdgcn_mfma_f32_16x16x32_bf16(Bt[n][k], At[m][k], acc[ai][bj][m][n], 0, 0, 0); __builtin_amdgcn_s_setprio(0); } while (0)
; #define PG8_WAIT_V(n) asm volatile("s_waitcnt vmcnt(" #n ")" ::: "memory")
; #define PG8_WAIT_L(n) asm volatile("s_waitcnt lgkmcnt(" #n ")" ::: "memory")
; #define PG8_BAR __builtin_amdgcn_s_barrier()
; #define PG8_SCHED __builtin_amdgcn_sched_barrier(0)
; template <class Epi, class Sched>
; __device__ __forceinline__ void gemm_phase(LAS unsigned char* lds, const Gemm g, const Sched& S, const Epi& E) {
;     ...
;             PG8_WAIT_V(6); PG8_BAR; PG8_MMA(1, 1, At, B1); PG8_BAR;
;             PG8_LDB(B0, 1, 0); PG8_SCHED; PG8_LDA(At, 1, 0); PG8_STAGE(PG8_SA(0, 1), a2 + hstepA, voffA);
;             PG8_WAIT_L(8); PG8_BAR; PG8_WAIT_L(0); PG8_MMA(0, 0, At, B0); PG8_BAR; PG8_SCHED;
;             PG8_LDB(B1, 1, 1); PG8_STAGE(PG8_SB(1, 0), b3, voffB);
;             PG8_BAR; PG8_WAIT_L(0); PG8_MMA(0, 1, At, B1); PG8_BAR;
;             PG8_LDA(At, 1, 1); PG8_STAGE(PG8_SA(1, 0), a3, voffA);
;             PG8_BAR; PG8_WAIT_L(0); PG8_MMA(1, 0, At, B0); PG8_BAR; PG8_SCHED;
	s_mov_b32 m0, s68
	v_lshl_add_u64 v[138:139], v[202:203], 0, s[6:7]
	global_load_lds_dwordx4 v[138:139], off
	v_lshl_add_u64 v[138:139], v[202:203], 0, s[8:9]
	s_mov_b32 m0, s66
	s_nop 0
	global_load_lds_dwordx4 v[138:139], off
	s_waitcnt vmcnt(6)
	s_barrier
	s_setprio 1
	v_mfma_f32_16x16x32_bf16 v[52:55], v[186:189], v[154:157], v[52:55]
	v_mfma_f32_16x16x32_bf16 v[44:47], v[194:197], v[154:157], v[44:47]
	v_mfma_f32_16x16x32_bf16 v[36:39], v[186:189], v[162:165], v[36:39]
	v_mfma_f32_16x16x32_bf16 v[28:31], v[194:197], v[162:165], v[28:31]
	v_mfma_f32_16x16x32_bf16 v[20:23], v[186:189], v[170:173], v[20:23]
	v_mfma_f32_16x16x32_bf16 v[12:15], v[194:197], v[170:173], v[12:15]
	v_mfma_f32_16x16x32_bf16 v[4:7], v[186:189], v[178:181], v[4:7]
	v_mfma_f32_16x16x32_bf16 v[0:3], v[194:197], v[178:181], v[0:3]
	v_mfma_f32_16x16x32_bf16 v[52:55], v[190:193], v[158:161], v[52:55]
	v_mfma_f32_16x16x32_bf16 v[44:47], v[198:201], v[158:161], v[44:47]
	v_mfma_f32_16x16x32_bf16 v[36:39], v[190:193], v[166:169], v[36:39]
	v_mfma_f32_16x16x32_bf16 v[28:31], v[198:201], v[166:169], v[28:31]
	v_mfma_f32_16x16x32_bf16 v[20:23], v[190:193], v[174:177], v[20:23]
	v_mfma_f32_16x16x32_bf16 v[12:15], v[198:201], v[174:177], v[12:15]
	v_mfma_f32_16x16x32_bf16 v[4:7], v[190:193], v[182:185], v[4:7]
	v_mfma_f32_16x16x32_bf16 v[0:3], v[198:201], v[182:185], v[0:3]
	s_setprio 0
	v_add_u32_e32 v137, s65, v132
	s_barrier
	ds_read_b128 v[138:141], v137
	ds_read_b128 v[142:145], v137 offset:1024
	ds_read_b128 v[146:149], v137 offset:2048
	ds_read_b128 v[150:153], v137 offset:3072
	s_mov_b32 m0, s38
	v_lshl_add_u64 v[186:187], v[204:205], 0, s[6:7]
	ds_read_b128 v[154:157], v133 offset:32768
	ds_read_b128 v[158:161], v133 offset:33792
	ds_read_b128 v[162:165], v133 offset:34816
	ds_read_b128 v[166:169], v133 offset:35840
	ds_read_b128 v[170:173], v133 offset:36864
	ds_read_b128 v[174:177], v133 offset:37888
	ds_read_b128 v[178:181], v133 offset:38912
	ds_read_b128 v[182:185], v133 offset:39936
	global_load_lds_dwordx4 v[186:187], off
	v_lshl_add_u64 v[186:187], v[204:205], 0, s[8:9]
	s_mov_b32 m0, s39
	s_nop 0
	global_load_lds_dwordx4 v[186:187], off
	s_waitcnt lgkmcnt(8)
	s_barrier
	s_waitcnt lgkmcnt(0)
	s_setprio 1
	s_waitcnt lgkmcnt(0)
	v_mfma_f32_16x16x32_bf16 v[124:127], v[138:141], v[154:157], v[124:127]
	v_mfma_f32_16x16x32_bf16 v[120:123], v[146:149], v[154:157], v[120:123]
	v_mfma_f32_16x16x32_bf16 v[112:115], v[138:141], v[162:165], v[112:115]
	v_mfma_f32_16x16x32_bf16 v[104:107], v[146:149], v[162:165], v[104:107]
	v_mfma_f32_16x16x32_bf16 v[96:99], v[138:141], v[170:173], v[96:99]
	v_mfma_f32_16x16x32_bf16 v[88:91], v[146:149], v[170:173], v[88:91]
	v_mfma_f32_16x16x32_bf16 v[80:83], v[138:141], v[178:181], v[80:83]
	v_mfma_f32_16x16x32_bf16 v[72:75], v[146:149], v[178:181], v[72:75]
	v_mfma_f32_16x16x32_bf16 v[124:127], v[142:145], v[158:161], v[124:127]
	v_mfma_f32_16x16x32_bf16 v[120:123], v[150:153], v[158:161], v[120:123]
	v_mfma_f32_16x16x32_bf16 v[112:115], v[142:145], v[166:169], v[112:115]
	v_mfma_f32_16x16x32_bf16 v[104:107], v[150:153], v[166:169], v[104:107]
	v_mfma_f32_16x16x32_bf16 v[96:99], v[142:145], v[174:177], v[96:99]
	v_mfma_f32_16x16x32_bf16 v[88:91], v[150:153], v[174:177], v[88:91]
	v_mfma_f32_16x16x32_bf16 v[80:83], v[142:145], v[182:185], v[80:83]
	v_mfma_f32_16x16x32_bf16 v[72:75], v[150:153], v[182:185], v[72:75]
	s_setprio 0
	s_barrier
	s_mov_b32 m0, s64
	v_add_u32_e32 v137, s63, v132
	v_lshl_add_u64 v[206:207], v[202:203], 0, s[10:11]
	ds_read_b128 v[186:189], v137
	ds_read_b128 v[190:193], v137 offset:1024
	ds_read_b128 v[194:197], v137 offset:2048
	ds_read_b128 v[198:201], v137 offset:3072
	global_load_lds_dwordx4 v[206:207], off
	v_lshl_add_u64 v[206:207], v[202:203], 0, s[16:17]
	s_mov_b32 m0, s71
	s_nop 0
	global_load_lds_dwordx4 v[206:207], off
	s_barrier
	s_waitcnt lgkmcnt(0)
	s_setprio 1
	s_waitcnt lgkmcnt(0)
	v_mfma_f32_16x16x32_bf16 v[116:119], v[186:189], v[154:157], v[116:119]
	v_mfma_f32_16x16x32_bf16 v[108:111], v[194:197], v[154:157], v[108:111]
	v_mfma_f32_16x16x32_bf16 v[100:103], v[186:189], v[162:165], v[100:103]
	v_mfma_f32_16x16x32_bf16 v[92:95], v[194:197], v[162:165], v[92:95]
	v_mfma_f32_16x16x32_bf16 v[84:87], v[186:189], v[170:173], v[84:87]
	v_mfma_f32_16x16x32_bf16 v[76:79], v[194:197], v[170:173], v[76:79]
	v_mfma_f32_16x16x32_bf16 v[68:71], v[186:189], v[178:181], v[68:71]
	v_mfma_f32_16x16x32_bf16 v[64:67], v[194:197], v[178:181], v[64:67]
	v_mfma_f32_16x16x32_bf16 v[116:119], v[190:193], v[158:161], v[116:119]
	v_mfma_f32_16x16x32_bf16 v[108:111], v[198:201], v[158:161], v[108:111]
	v_mfma_f32_16x16x32_bf16 v[100:103], v[190:193], v[166:169], v[100:103]
	v_mfma_f32_16x16x32_bf16 v[92:95], v[198:201], v[166:169], v[92:95]
	v_mfma_f32_16x16x32_bf16 v[84:87], v[190:193], v[174:177], v[84:87]
	v_mfma_f32_16x16x32_bf16 v[76:79], v[198:201], v[174:177], v[76:79]
	v_mfma_f32_16x16x32_bf16 v[68:71], v[190:193], v[182:185], v[68:71]
	v_mfma_f32_16x16x32_bf16 v[64:67], v[198:201], v[182:185], v[64:67]
	s_setprio 0
	s_mov_b32 m0, s40
	v_lshl_add_u64 v[206:207], v[204:205], 0, s[10:11]
	s_barrier
	ds_read_b128 v[154:157], v133 offset:49152
	ds_read_b128 v[158:161], v133 offset:50176
	ds_read_b128 v[162:165], v133 offset:51200
	ds_read_b128 v[166:169], v133 offset:52224
	ds_read_b128 v[170:173], v133 offset:53248
	ds_read_b128 v[174:177], v133 offset:54272
	ds_read_b128 v[178:181], v133 offset:55296
	ds_read_b128 v[182:185], v133 offset:56320
	global_load_lds_dwordx4 v[206:207], off
	v_lshl_add_u64 v[204:205], v[204:205], 0, s[16:17]
	s_mov_b32 m0, s41
	s_nop 0
	global_load_lds_dwordx4 v[204:205], off
	s_barrier
; #define PG8_STAGE(bufoff, gbase, voff) do { _Pragma("unroll") for (int _i = 0; _i < 2; ++_i) \
;         __builtin_amdgcn_global_load_lds((const unsigned*)((const char*)(gbase) + (size_t)_i * r64##voff + (voff)), (LAS unsigned*)(lds + (bufoff) + ldsw + _i * 8192), 16, 0, 0); } while (0)
; #define PG8_MMA(ai, bj, At, Bt) do { __builtin_amdgcn_s_setprio(1); _Pragma("unroll") for (int m = 0; m < 4; ++m) _Pragma("unroll") for (int n = 0; n < 2; ++n) _Pragma("unroll") for (int k = 0; k < 2; ++k) \
;         acc[ai][bj][m][n] = __builtin_amdgcn_mfma_f32_16x16x32_bf16(Bt[n][k], At[m][k], acc[ai][bj][m][n], 0, 0, 0); __builtin_amdgcn_s_setprio(0); } while (0)
; #define PG8_WAIT_V(n) asm volatile("s_waitcnt vmcnt(" #n ")" ::: "memory")
; #define PG8_WAIT_L(n) asm volatile("s_waitcnt lgkmcnt(" #n ")" ::: "memory")
; #define PG8_BAR __builtin_amdgcn_s_barrier()
; #define PG8_SCHED __builtin_amdgcn_sched_barrier(0)
; template <class Epi, class Sched>
; __device__ __forceinline__ void gemm_phase(LAS unsigned char* lds, const Gemm g, const Sched& S, const Epi& E) {
;     ...
;             PG8_BAR; PG8_WAIT_L(0); PG8_MMA(1, 0, At, B0); PG8_BAR; PG8_SCHED;
;             PG8_STAGE(PG8_SB(1, 1), b3 + hstepB, voffB);
;             PG8_WAIT_V(6); PG8_BAR; PG8_MMA(1, 1, At, B1); PG8_BAR;
;         }
;     __device__ __forceinline__ void operator()(const f32x4 (&acc)[2][2][4][2], const pg8::Unit& u, int wr_, int wc_, int fr_, int fq_) const {
;     ...
; #pragma unroll
;         for (int ai = 0; ai < 2; ++ai)
; #pragma unroll
;             for (int m = 0; m < 4; ++m) { const size_t ro = (size_t)(row0 + ai * 128 + m * 16) * 2048;
; #pragma unroll
;                 for (int bj = 0; bj < 2; ++bj)
; #pragma unroll
;                     for (int n = 0; n < 2; ++n) { const int col = col0 + bj * 128 + n * 16;
;                         const f32x4 v = *(const f32x4*)(gate + col) * acc[ai][bj][m][n];
;                         __hip_atomic_fetch_add(dst + ro + col, v[0], __ATOMIC_RELAXED, __HIP_MEMORY_SCOPE_AGENT); __hip_atomic_fetch_add(dst + ro + col + 1, v[1], __ATOMIC_RELAXED, __HIP_MEMORY_SCOPE_AGENT);
;                         __hip_atomic_fetch_add(dst + ro + col + 2, v[2], __ATOMIC_RELAXED, __HIP_MEMORY_SCOPE_AGENT); __hip_atomic_fetch_add(dst + ro + col + 3, v[3], __ATOMIC_RELAXED, __HIP_MEMORY_SCOPE_AGENT); } }
	s_waitcnt lgkmcnt(0)
	s_setprio 1
	s_waitcnt lgkmcnt(0)
	v_mfma_f32_16x16x32_bf16 v[60:63], v[138:141], v[154:157], v[60:63]
	v_mfma_f32_16x16x32_bf16 v[56:59], v[146:149], v[154:157], v[56:59]
	v_mfma_f32_16x16x32_bf16 v[48:51], v[138:141], v[162:165], v[48:51]
	v_mfma_f32_16x16x32_bf16 v[40:43], v[146:149], v[162:165], v[40:43]
	v_mfma_f32_16x16x32_bf16 v[32:35], v[138:141], v[170:173], v[32:35]
	v_mfma_f32_16x16x32_bf16 v[24:27], v[146:149], v[170:173], v[24:27]
	v_mfma_f32_16x16x32_bf16 v[16:19], v[138:141], v[178:181], v[16:19]
	v_mfma_f32_16x16x32_bf16 v[8:11], v[146:149], v[178:181], v[8:11]
	v_mfma_f32_16x16x32_bf16 v[60:63], v[142:145], v[158:161], v[60:63]
	v_mfma_f32_16x16x32_bf16 v[56:59], v[150:153], v[158:161], v[56:59]
	v_mfma_f32_16x16x32_bf16 v[48:51], v[142:145], v[166:169], v[48:51]
	v_mfma_f32_16x16x32_bf16 v[40:43], v[150:153], v[166:169], v[40:43]
	v_mfma_f32_16x16x32_bf16 v[32:35], v[142:145], v[174:177], v[32:35]
	v_mfma_f32_16x16x32_bf16 v[24:27], v[150:153], v[174:177], v[24:27]
	v_mfma_f32_16x16x32_bf16 v[16:19], v[142:145], v[182:185], v[16:19]
	v_mfma_f32_16x16x32_bf16 v[8:11], v[150:153], v[182:185], v[8:11]
	s_setprio 0
	s_barrier
	s_mov_b32 m0, s69
	v_lshl_add_u64 v[138:139], v[202:203], 0, s[18:19]
	global_load_lds_dwordx4 v[138:139], off
	v_lshl_add_u64 v[138:139], v[202:203], 0, s[20:21]
	s_mov_b32 m0, s67
	s_nop 0
	global_load_lds_dwordx4 v[138:139], off
	s_waitcnt vmcnt(6)
	s_barrier
	s_setprio 1
	v_mfma_f32_16x16x32_bf16 v[52:55], v[186:189], v[154:157], v[52:55]
	v_mfma_f32_16x16x32_bf16 v[44:47], v[194:197], v[154:157], v[44:47]
	v_mfma_f32_16x16x32_bf16 v[36:39], v[186:189], v[162:165], v[36:39]
	v_mfma_f32_16x16x32_bf16 v[28:31], v[194:197], v[162:165], v[28:31]
	v_mfma_f32_16x16x32_bf16 v[20:23], v[186:189], v[170:173], v[20:23]
	v_mfma_f32_16x16x32_bf16 v[12:15], v[194:197], v[170:173], v[12:15]
	v_mfma_f32_16x16x32_bf16 v[4:7], v[186:189], v[178:181], v[4:7]
	v_mfma_f32_16x16x32_bf16 v[0:3], v[194:197], v[178:181], v[0:3]
	v_mfma_f32_16x16x32_bf16 v[52:55], v[190:193], v[158:161], v[52:55]
	v_mfma_f32_16x16x32_bf16 v[44:47], v[198:201], v[158:161], v[44:47]
	v_mfma_f32_16x16x32_bf16 v[36:39], v[190:193], v[166:169], v[36:39]
	v_mfma_f32_16x16x32_bf16 v[28:31], v[198:201], v[166:169], v[28:31]
	v_mfma_f32_16x16x32_bf16 v[20:23], v[190:193], v[174:177], v[20:23]
	v_mfma_f32_16x16x32_bf16 v[12:15], v[198:201], v[174:177], v[12:15]
	v_mfma_f32_16x16x32_bf16 v[4:7], v[190:193], v[182:185], v[4:7]
	v_mfma_f32_16x16x32_bf16 v[0:3], v[198:201], v[182:185], v[0:3]
	s_setprio 0
	s_addk_i32 s2, 0x100
	s_cmpk_eq_i32 s2, 0x700
	s_cselect_b64 s[56:57], -1, 0
	s_cmpk_lt_i32 s2, 0x800
	s_barrier
	s_cbranch_scc1 .LBB0_485
	s_add_u32 s48, s52, 0x66b4000
	s_addc_u32 s49, s53, 0
	v_mov_b32_e32 v128, v222
	s_add_u32 s46, s50, 0xfde80000
	s_addc_u32 s47, s51, -1
	v_lshrrev_b32_e32 v130, 1, v128
	v_lshrrev_b32_e32 v131, 2, v128
	s_lshl_b32 s2, s44, 8
	v_and_b32_e32 v130, 0x60, v130
	v_and_b32_e32 v131, 12, v131
	v_or3_b32 v142, v130, s2, v131
	v_ashrrev_i32_e32 v143, 31, v142
	v_lshlrev_b64 v[144:145], 2, v[142:143]
	v_lshl_add_u64 v[130:131], s[48:49], 0, v[144:145]
	v_ashrrev_i32_e32 v132, 2, v128
	s_lshl_b32 s2, s12, 8
	v_and_b32_e32 v132, 0xffffffc0, v132
	v_and_or_b32 v128, v128, 15, s2
	v_add_u32_e32 v146, v128, v132
	v_ashrrev_i32_e32 v147, 31, v146
	v_lshlrev_b64 v[134:135], 13, v[146:147]
	v_or_b32_e32 v132, 16, v142
	v_lshl_add_u64 v[134:135], s[46:47], 0, v[134:135]
	v_ashrrev_i32_e32 v133, 31, v132
	v_lshl_add_u64 v[134:135], v[134:135], 0, v[144:145]
	v_lshl_add_u64 v[132:133], v[132:133], 2, s[48:49]
	s_cmpk_lt_u32 s34, 0x100
	s_mov_b32 s98, 0x20000
	s_mov_b32 s99, 0
	s_mov_b32 s100, 0xa0000
	s_mov_b32 s101, 0
	global_load_dwordx4 v[138:141], v[130:131], off
	global_load_dwordx4 v[148:151], v[130:131], off offset:64
	global_load_dwordx4 v[152:155], v[130:131], off offset:512
	global_load_dwordx4 v[156:159], v[130:131], off offset:576
	s_waitcnt vmcnt(0)
	v_pk_mul_f32 v[124:125], v[124:125], v[138:139]
	v_pk_mul_f32 v[126:127], v[126:127], v[140:141]
	global_atomic_add_f32 v[134:135], v124, off
	global_atomic_add_f32 v[134:135], v125, off offset:4
	global_atomic_add_f32 v[134:135], v126, off offset:8
	global_atomic_add_f32 v[134:135], v127, off offset:12
	v_pk_mul_f32 v[120:121], v[120:121], v[148:149]
	v_pk_mul_f32 v[122:123], v[122:123], v[150:151]
	global_atomic_add_f32 v[134:135], v120, off offset:64
	global_atomic_add_f32 v[134:135], v121, off offset:68
	global_atomic_add_f32 v[134:135], v122, off offset:72
	global_atomic_add_f32 v[134:135], v123, off offset:76
	v_pk_mul_f32 v[116:117], v[116:117], v[152:153]
	v_pk_mul_f32 v[118:119], v[118:119], v[154:155]
	global_atomic_add_f32 v[134:135], v116, off offset:512
	global_atomic_add_f32 v[134:135], v117, off offset:516
	global_atomic_add_f32 v[134:135], v118, off offset:520
	global_atomic_add_f32 v[134:135], v119, off offset:524
	v_pk_mul_f32 v[108:109], v[108:109], v[156:157]
	v_pk_mul_f32 v[110:111], v[110:111], v[158:159]
	global_atomic_add_f32 v[134:135], v108, off offset:576
	global_atomic_add_f32 v[134:135], v109, off offset:580
	global_atomic_add_f32 v[134:135], v110, off offset:584
	global_atomic_add_f32 v[134:135], v111, off offset:588
	v_lshl_add_u64 v[134:135], v[134:135], 0, s[98:99]
	v_pk_mul_f32 v[112:113], v[112:113], v[138:139]
	v_pk_mul_f32 v[114:115], v[114:115], v[140:141]
	global_atomic_add_f32 v[134:135], v112, off
	global_atomic_add_f32 v[134:135], v113, off offset:4
	global_atomic_add_f32 v[134:135], v114, off offset:8
	global_atomic_add_f32 v[134:135], v115, off offset:12
	v_pk_mul_f32 v[104:105], v[104:105], v[148:149]
;     __device__ __forceinline__ void operator()(const f32x4 (&acc)[2][2][4][2], const pg8::Unit& u, int wr_, int wc_, int fr_, int fq_) const {
;     ...
; #pragma unroll
;         for (int ai = 0; ai < 2; ++ai)
; #pragma unroll
;             for (int m = 0; m < 4; ++m) { const size_t ro = (size_t)(row0 + ai * 128 + m * 16) * 2048;
; #pragma unroll
;                 for (int bj = 0; bj < 2; ++bj)
; #pragma unroll
;                     for (int n = 0; n < 2; ++n) { const int col = col0 + bj * 128 + n * 16;
;                         const f32x4 v = *(const f32x4*)(gate + col) * acc[ai][bj][m][n];
;                         __hip_atomic_fetch_add(dst + ro + col, v[0], __ATOMIC_RELAXED, __HIP_MEMORY_SCOPE_AGENT); __hip_atomic_fetch_add(dst + ro + col + 1, v[1], __ATOMIC_RELAXED, __HIP_MEMORY_SCOPE_AGENT);
;                         __hip_atomic_fetch_add(dst + ro + col + 2, v[2], __ATOMIC_RELAXED, __HIP_MEMORY_SCOPE_AGENT); __hip_atomic_fetch_add(dst + ro + col + 3, v[3], __ATOMIC_RELAXED, __HIP_MEMORY_SCOPE_AGENT); } }
	v_pk_mul_f32 v[106:107], v[106:107], v[150:151]
	global_atomic_add_f32 v[134:135], v104, off offset:64
	global_atomic_add_f32 v[134:135], v105, off offset:68
	global_atomic_add_f32 v[134:135], v106, off offset:72
	global_atomic_add_f32 v[134:135], v107, off offset:76
	v_pk_mul_f32 v[100:101], v[100:101], v[152:153]
	v_pk_mul_f32 v[102:103], v[102:103], v[154:155]
	global_atomic_add_f32 v[134:135], v100, off offset:512
	global_atomic_add_f32 v[134:135], v101, off offset:516
	global_atomic_add_f32 v[134:135], v102, off offset:520
	global_atomic_add_f32 v[134:135], v103, off offset:524
	v_pk_mul_f32 v[92:93], v[92:93], v[156:157]
	v_pk_mul_f32 v[94:95], v[94:95], v[158:159]
	global_atomic_add_f32 v[134:135], v92, off offset:576
	global_atomic_add_f32 v[134:135], v93, off offset:580
	global_atomic_add_f32 v[134:135], v94, off offset:584
	global_atomic_add_f32 v[134:135], v95, off offset:588
	v_lshl_add_u64 v[134:135], v[134:135], 0, s[98:99]
	v_pk_mul_f32 v[96:97], v[96:97], v[138:139]
	v_pk_mul_f32 v[98:99], v[98:99], v[140:141]
	global_atomic_add_f32 v[134:135], v96, off
	global_atomic_add_f32 v[134:135], v97, off offset:4
	global_atomic_add_f32 v[134:135], v98, off offset:8
	global_atomic_add_f32 v[134:135], v99, off offset:12
	v_pk_mul_f32 v[88:89], v[88:89], v[148:149]
	v_pk_mul_f32 v[90:91], v[90:91], v[150:151]
	global_atomic_add_f32 v[134:135], v88, off offset:64
	global_atomic_add_f32 v[134:135], v89, off offset:68
	global_atomic_add_f32 v[134:135], v90, off offset:72
	global_atomic_add_f32 v[134:135], v91, off offset:76
	v_pk_mul_f32 v[84:85], v[84:85], v[152:153]
	v_pk_mul_f32 v[86:87], v[86:87], v[154:155]
	global_atomic_add_f32 v[134:135], v84, off offset:512
	global_atomic_add_f32 v[134:135], v85, off offset:516
	global_atomic_add_f32 v[134:135], v86, off offset:520
	global_atomic_add_f32 v[134:135], v87, off offset:524
	v_pk_mul_f32 v[76:77], v[76:77], v[156:157]
	v_pk_mul_f32 v[78:79], v[78:79], v[158:159]
	global_atomic_add_f32 v[134:135], v76, off offset:576
	global_atomic_add_f32 v[134:135], v77, off offset:580
	global_atomic_add_f32 v[134:135], v78, off offset:584
	global_atomic_add_f32 v[134:135], v79, off offset:588
	v_lshl_add_u64 v[134:135], v[134:135], 0, s[98:99]
	v_pk_mul_f32 v[80:81], v[80:81], v[138:139]
	v_pk_mul_f32 v[82:83], v[82:83], v[140:141]
	global_atomic_add_f32 v[134:135], v80, off
	global_atomic_add_f32 v[134:135], v81, off offset:4
	global_atomic_add_f32 v[134:135], v82, off offset:8
	global_atomic_add_f32 v[134:135], v83, off offset:12
	v_pk_mul_f32 v[72:73], v[72:73], v[148:149]
	v_pk_mul_f32 v[74:75], v[74:75], v[150:151]
	global_atomic_add_f32 v[134:135], v72, off offset:64
	global_atomic_add_f32 v[134:135], v73, off offset:68
	global_atomic_add_f32 v[134:135], v74, off offset:72
	global_atomic_add_f32 v[134:135], v75, off offset:76
	v_pk_mul_f32 v[68:69], v[68:69], v[152:153]
	v_pk_mul_f32 v[70:71], v[70:71], v[154:155]
	global_atomic_add_f32 v[134:135], v68, off offset:512
	global_atomic_add_f32 v[134:135], v69, off offset:516
	global_atomic_add_f32 v[134:135], v70, off offset:520
	global_atomic_add_f32 v[134:135], v71, off offset:524
	v_pk_mul_f32 v[64:65], v[64:65], v[156:157]
	v_pk_mul_f32 v[66:67], v[66:67], v[158:159]
	global_atomic_add_f32 v[134:135], v64, off offset:576
	global_atomic_add_f32 v[134:135], v65, off offset:580
	global_atomic_add_f32 v[134:135], v66, off offset:584
	global_atomic_add_f32 v[134:135], v67, off offset:588
	v_lshl_add_u64 v[134:135], v[134:135], 0, s[100:101]
	v_pk_mul_f32 v[60:61], v[60:61], v[138:139]
	v_pk_mul_f32 v[62:63], v[62:63], v[140:141]
	global_atomic_add_f32 v[134:135], v60, off
	global_atomic_add_f32 v[134:135], v61, off offset:4
	global_atomic_add_f32 v[134:135], v62, off offset:8
	global_atomic_add_f32 v[134:135], v63, off offset:12
	v_pk_mul_f32 v[56:57], v[56:57], v[148:149]
	v_pk_mul_f32 v[58:59], v[58:59], v[150:151]
	global_atomic_add_f32 v[134:135], v56, off offset:64
	global_atomic_add_f32 v[134:135], v57, off offset:68
	global_atomic_add_f32 v[134:135], v58, off offset:72
	global_atomic_add_f32 v[134:135], v59, off offset:76
	v_pk_mul_f32 v[52:53], v[52:53], v[152:153]
	v_pk_mul_f32 v[54:55], v[54:55], v[154:155]
	global_atomic_add_f32 v[134:135], v52, off offset:512
	global_atomic_add_f32 v[134:135], v53, off offset:516
;     __device__ __forceinline__ void operator()(const f32x4 (&acc)[2][2][4][2], const pg8::Unit& u, int wr_, int wc_, int fr_, int fq_) const {
;     ...
; #pragma unroll
;         for (int ai = 0; ai < 2; ++ai)
; #pragma unroll
;             for (int m = 0; m < 4; ++m) { const size_t ro = (size_t)(row0 + ai * 128 + m * 16) * 2048;
; #pragma unroll
;                 for (int bj = 0; bj < 2; ++bj)
; #pragma unroll
;                     for (int n = 0; n < 2; ++n) { const int col = col0 + bj * 128 + n * 16;
;                         const f32x4 v = *(const f32x4*)(gate + col) * acc[ai][bj][m][n];
;                         __hip_atomic_fetch_add(dst + ro + col, v[0], __ATOMIC_RELAXED, __HIP_MEMORY_SCOPE_AGENT); __hip_atomic_fetch_add(dst + ro + col + 1, v[1], __ATOMIC_RELAXED, __HIP_MEMORY_SCOPE_AGENT);
;                         __hip_atomic_fetch_add(dst + ro + col + 2, v[2], __ATOMIC_RELAXED, __HIP_MEMORY_SCOPE_AGENT); __hip_atomic_fetch_add(dst + ro + col + 3, v[3], __ATOMIC_RELAXED, __HIP_MEMORY_SCOPE_AGENT); } }
	global_atomic_add_f32 v[134:135], v54, off offset:520
	global_atomic_add_f32 v[134:135], v55, off offset:524
	v_pk_mul_f32 v[44:45], v[44:45], v[156:157]
	v_pk_mul_f32 v[46:47], v[46:47], v[158:159]
	global_atomic_add_f32 v[134:135], v44, off offset:576
	global_atomic_add_f32 v[134:135], v45, off offset:580
	global_atomic_add_f32 v[134:135], v46, off offset:584
	global_atomic_add_f32 v[134:135], v47, off offset:588
	v_lshl_add_u64 v[134:135], v[134:135], 0, s[98:99]
	v_pk_mul_f32 v[48:49], v[48:49], v[138:139]
	v_pk_mul_f32 v[50:51], v[50:51], v[140:141]
	global_atomic_add_f32 v[134:135], v48, off
	global_atomic_add_f32 v[134:135], v49, off offset:4
	global_atomic_add_f32 v[134:135], v50, off offset:8
	global_atomic_add_f32 v[134:135], v51, off offset:12
	v_pk_mul_f32 v[40:41], v[40:41], v[148:149]
	v_pk_mul_f32 v[42:43], v[42:43], v[150:151]
	global_atomic_add_f32 v[134:135], v40, off offset:64
	global_atomic_add_f32 v[134:135], v41, off offset:68
	global_atomic_add_f32 v[134:135], v42, off offset:72
	global_atomic_add_f32 v[134:135], v43, off offset:76
	v_pk_mul_f32 v[36:37], v[36:37], v[152:153]
	v_pk_mul_f32 v[38:39], v[38:39], v[154:155]
	global_atomic_add_f32 v[134:135], v36, off offset:512
	global_atomic_add_f32 v[134:135], v37, off offset:516
	global_atomic_add_f32 v[134:135], v38, off offset:520
	global_atomic_add_f32 v[134:135], v39, off offset:524
	v_pk_mul_f32 v[28:29], v[28:29], v[156:157]
	v_pk_mul_f32 v[30:31], v[30:31], v[158:159]
	global_atomic_add_f32 v[134:135], v28, off offset:576
	global_atomic_add_f32 v[134:135], v29, off offset:580
	global_atomic_add_f32 v[134:135], v30, off offset:584
	global_atomic_add_f32 v[134:135], v31, off offset:588
	v_lshl_add_u64 v[134:135], v[134:135], 0, s[98:99]
	v_pk_mul_f32 v[32:33], v[32:33], v[138:139]
	v_pk_mul_f32 v[34:35], v[34:35], v[140:141]
	global_atomic_add_f32 v[134:135], v32, off
	global_atomic_add_f32 v[134:135], v33, off offset:4
	global_atomic_add_f32 v[134:135], v34, off offset:8
	global_atomic_add_f32 v[134:135], v35, off offset:12
	v_pk_mul_f32 v[24:25], v[24:25], v[148:149]
	v_pk_mul_f32 v[26:27], v[26:27], v[150:151]
	global_atomic_add_f32 v[134:135], v24, off offset:64
	global_atomic_add_f32 v[134:135], v25, off offset:68
	global_atomic_add_f32 v[134:135], v26, off offset:72
	global_atomic_add_f32 v[134:135], v27, off offset:76
	v_pk_mul_f32 v[20:21], v[20:21], v[152:153]
	v_pk_mul_f32 v[22:23], v[22:23], v[154:155]
	global_atomic_add_f32 v[134:135], v20, off offset:512
	global_atomic_add_f32 v[134:135], v21, off offset:516
	global_atomic_add_f32 v[134:135], v22, off offset:520
	global_atomic_add_f32 v[134:135], v23, off offset:524
	v_pk_mul_f32 v[12:13], v[12:13], v[156:157]
	v_pk_mul_f32 v[14:15], v[14:15], v[158:159]
	global_atomic_add_f32 v[134:135], v12, off offset:576
	global_atomic_add_f32 v[134:135], v13, off offset:580
	global_atomic_add_f32 v[134:135], v14, off offset:584
	global_atomic_add_f32 v[134:135], v15, off offset:588
	v_lshl_add_u64 v[134:135], v[134:135], 0, s[98:99]
	v_pk_mul_f32 v[16:17], v[16:17], v[138:139]
	v_pk_mul_f32 v[18:19], v[18:19], v[140:141]
	global_atomic_add_f32 v[134:135], v16, off
	global_atomic_add_f32 v[134:135], v17, off offset:4
	global_atomic_add_f32 v[134:135], v18, off offset:8
	global_atomic_add_f32 v[134:135], v19, off offset:12
	v_pk_mul_f32 v[8:9], v[8:9], v[148:149]
	v_pk_mul_f32 v[10:11], v[10:11], v[150:151]
	global_atomic_add_f32 v[134:135], v8, off offset:64
	global_atomic_add_f32 v[134:135], v9, off offset:68
	global_atomic_add_f32 v[134:135], v10, off offset:72
	global_atomic_add_f32 v[134:135], v11, off offset:76
	v_pk_mul_f32 v[4:5], v[4:5], v[152:153]
	v_pk_mul_f32 v[6:7], v[6:7], v[154:155]
	global_atomic_add_f32 v[134:135], v4, off offset:512
	global_atomic_add_f32 v[134:135], v5, off offset:516
	global_atomic_add_f32 v[134:135], v6, off offset:520
	global_atomic_add_f32 v[134:135], v7, off offset:524
	v_pk_mul_f32 v[0:1], v[0:1], v[156:157]
	v_pk_mul_f32 v[2:3], v[2:3], v[158:159]
	global_atomic_add_f32 v[134:135], v0, off offset:576
	global_atomic_add_f32 v[134:135], v1, off offset:580
	global_atomic_add_f32 v[134:135], v2, off offset:584
	global_atomic_add_f32 v[134:135], v3, off offset:588
	s_cbranch_scc0 .LBB0_481
	s_barrier
	s_branch .LBB0_481
